# stream prologues issue K-tile 0 and K-tile 1 staging together (first wait vmcnt 2 -> 8)
# speedup vs baseline: 1.0015x; 1.0015x over previous
.Lsprio_0:
	s_cmp_lg_u32 s99, 0
	s_mov_b32 m0, s63
	s_nop 0
	global_load_lds_dwordx4 v0, s[8:9]
	s_add_u32 s8, s4, 0x80
	s_mov_b32 m0, s64
	s_nop 0
	global_load_lds_dwordx4 v0, s[24:25]
	s_addc_u32 s9, s5, 0
	s_sub_u32 s2, 0, s38
	s_subb_u32 s24, 0, s39
	s_add_u32 s2, s14, s2
	s_addc_u32 s15, s15, s24
	s_add_u32 s14, s2, 0x80
	s_addc_u32 s15, s15, 0
	s_add_i32 s65, s53, 0x8000
	s_add_i32 s66, s53, 0xa000
	s_mov_b32 m0, s65
	s_nop 0
	global_load_lds_dwordx4 v160, s[8:9]
	s_add_u32 s8, s10, 0x80
	s_addc_u32 s9, s11, 0
	s_mov_b32 m0, s66
	s_nop 0
	global_load_lds_dwordx4 v160, s[14:15]
	s_add_u32 s10, s12, 0x80
	v_lshlrev_b32_e32 v2, 2, v2
	s_addc_u32 s11, s13, 0
	s_add_i32 s67, s53, 0x1c000
	s_mov_b32 m0, s67
	s_nop 0
	global_load_lds_dwordx4 v0, s[8:9]
	v_lshlrev_b32_e32 v3, 2, v3
	v_lshl_or_b32 v1, v1, 6, v6
	v_and_b32_e32 v2, 32, v2
	s_add_i32 s73, s53, 0x1e000
	s_mov_b32 m0, s73
	s_nop 0
	global_load_lds_dwordx4 v0, s[10:11]
	v_and_b32_e32 v3, 32, v3
	v_bitop3_b32 v1, v1, v4, v2 bitop3:0xde
	s_waitcnt vmcnt(8)
	s_barrier
	s_waitcnt vmcnt(6)
	s_add_i32 s78, s53, 0xc000
	s_add_i32 s79, s53, 0xe000
	v_readlane_b32 s2, v254, 0
	v_mov_b32_e32 v161, v0
	v_bitop3_b32 v3, v5, v7, v3 bitop3:0xde
	s_cmpk_lt_u32 s2, 0x100
	v_add_u32_e32 v0, 0, v1
	s_cselect_b64 s[24:25], -1, 0
	s_mov_b32 s27, 0
	v_add_u32_e32 v191, 0x10000, v0
	v_add_u32_e32 v192, 0x14000, v0
	v_add_u32_e32 v193, 0, v3
	v_mov_b32_e32 v194, 0x79797979
	v_mov_b32_e32 v195, 0x7f7f7f7f
	v_add_u32_e32 v196, 0x18000, v0
	v_add_u32_e32 v197, 0x1c000, v0
	s_mov_b32 s82, 0
	s_barrier
	s_branch .LBB0_234

.Lsprio_1:
	s_cmp_lg_u32 s99, 0
	v_add_lshl_u32 v4, v4, s14, 10
	s_add_u32 s14, s6, 0x80
	s_addc_u32 s15, s7, 0
	s_sub_u32 s16, 0, s18
	s_subb_u32 s26, 0, s19
	s_add_u32 s16, s8, s16
	s_addc_u32 s27, s9, s26
	s_add_u32 s26, s16, 0x80
	s_addc_u32 s27, s27, 0
	s_add_i32 s61, s53, 0x18000
	s_mov_b32 m0, s61
	s_nop 0
	global_load_lds_dwordx4 v0, s[14:15]
	s_add_i32 s62, s53, 0x1a000
	s_mov_b32 m0, s62
	s_nop 0
	global_load_lds_dwordx4 v0, s[26:27]
	s_add_u32 s14, s4, 0x80
	s_addc_u32 s15, s5, 0
	s_sub_u32 s16, 0, s38
	s_subb_u32 s26, 0, s39
	s_add_u32 s12, s12, s16
	s_addc_u32 s13, s13, s26
	s_add_u32 s12, s12, 0x80
	s_addc_u32 s13, s13, 0
	s_add_i32 s63, s53, 0x8000
	s_add_i32 s64, s53, 0xa000
	s_add_u32 s8, s8, 0x80
	s_mov_b32 m0, s63
	s_nop 0
	global_load_lds_dwordx4 v128, s[14:15]
	s_addc_u32 s9, s9, 0
	s_mov_b32 m0, s64
	s_nop 0
	global_load_lds_dwordx4 v128, s[12:13]
	s_add_u32 s10, s10, 0x80
	v_lshlrev_b32_e32 v2, 2, v2
	s_addc_u32 s11, s11, 0
	s_add_i32 s65, s53, 0x1c000
	s_mov_b32 m0, s65
	s_nop 0
	global_load_lds_dwordx4 v0, s[8:9]
	v_lshlrev_b32_e32 v3, 2, v3
	v_lshl_or_b32 v1, v1, 6, v6
	v_and_b32_e32 v2, 32, v2
	s_add_i32 s66, s53, 0x1e000
	s_mov_b32 m0, s66
	s_nop 0
	global_load_lds_dwordx4 v0, s[10:11]
	v_and_b32_e32 v3, 32, v3
	v_bitop3_b32 v1, v1, v4, v2 bitop3:0xde
	s_waitcnt vmcnt(8)
	s_barrier
	s_waitcnt vmcnt(6)
	s_add_i32 s67, s53, 0xc000
	s_add_i32 s68, s53, 0xe000
	v_readlane_b32 s8, v254, 0
	v_mov_b32_e32 v129, v0
	v_bitop3_b32 v3, v5, v7, v3 bitop3:0xde
	s_cmpk_lt_u32 s8, 0x100
	v_add_u32_e32 v0, 0, v1
	s_cselect_b64 s[26:27], -1, 0
	v_add_u32_e32 v135, 0x10000, v0
	v_add_u32_e32 v136, 0x14000, v0
	v_add_u32_e32 v137, 0, v3
	v_add_u32_e32 v138, 0x18000, v0
	v_add_u32_e32 v139, 0x1c000, v0
	s_mov_b32 s69, s17
	s_barrier
	s_branch .LBB0_253

.Lsprio_2:
	s_cmp_lg_u32 s99, 0
	s_mov_b32 m0, s65
	s_nop 0
	global_load_lds_dwordx4 v0, s[8:9]
	s_add_u32 s8, s4, 0x80
	s_mov_b32 m0, s66
	s_nop 0
	global_load_lds_dwordx4 v0, s[20:21]
	s_addc_u32 s9, s5, 0
	s_sub_u32 s2, 0, s46
	s_subb_u32 s20, 0, s47
	s_add_u32 s2, s14, s2
	s_addc_u32 s15, s15, s20
	s_add_u32 s14, s2, 0x80
	s_addc_u32 s15, s15, 0
	s_add_i32 s67, s53, 0x8000
	s_add_i32 s73, s53, 0xa000
	s_mov_b32 m0, s67
	s_nop 0
	global_load_lds_dwordx4 v128, s[8:9]
	s_add_u32 s8, s10, 0x80
	s_addc_u32 s9, s11, 0
	s_mov_b32 m0, s73
	s_nop 0
	global_load_lds_dwordx4 v128, s[14:15]
	s_add_u32 s10, s12, 0x80
	v_lshlrev_b32_e32 v2, 2, v2
	s_addc_u32 s11, s13, 0
	s_add_i32 s78, s53, 0x1c000
	s_mov_b32 m0, s78
	s_nop 0
	global_load_lds_dwordx4 v0, s[8:9]
	v_lshlrev_b32_e32 v3, 2, v3
	v_lshl_or_b32 v1, v1, 6, v6
	v_and_b32_e32 v2, 32, v2
	s_add_i32 s79, s53, 0x1e000
	s_mov_b32 m0, s79
	s_nop 0
	global_load_lds_dwordx4 v0, s[10:11]
	v_and_b32_e32 v3, 32, v3
	v_bitop3_b32 v1, v1, v4, v2 bitop3:0xde
	s_waitcnt vmcnt(8)
	s_barrier
	s_waitcnt vmcnt(6)
	s_add_i32 s82, s53, 0xc000
	s_add_i32 s83, s53, 0xe000
	v_readlane_b32 s2, v254, 0
	v_mov_b32_e32 v129, v0
	v_bitop3_b32 v3, v5, v7, v3 bitop3:0xde
	s_cmpk_lt_u32 s2, 0x100
	v_add_u32_e32 v0, 0, v1
	s_mov_b32 s21, 0
	s_cselect_b64 s[22:23], -1, 0
	v_add_u32_e32 v143, 0x10000, v0
	v_add_u32_e32 v144, 0x14000, v0
	v_add_u32_e32 v145, 0, v3
	v_add_u32_e32 v146, 0x18000, v0
	v_add_u32_e32 v147, 0x1c000, v0
	s_mov_b32 s34, s31
	s_mov_b32 s31, 0
	s_barrier
	s_branch .LBB0_272

.Lsprio_3:
	s_cmp_lg_u32 s99, 0
	s_mov_b32 m0, s61
	s_nop 0
	global_load_lds_dwordx4 v0, s[14:15]
	s_add_u32 s14, s4, 0x80
	s_mov_b32 m0, s62
	s_nop 0
	global_load_lds_dwordx4 v0, s[24:25]
	s_addc_u32 s15, s5, 0
	s_sub_u32 s0, 0, s42
	s_subb_u32 s2, 0, s43
	s_add_u32 s0, s12, s0
	s_addc_u32 s2, s13, s2
	s_add_u32 s12, s0, 0x80
	s_addc_u32 s13, s2, 0
	s_add_i32 s63, s53, 0x8000
	s_add_i32 s64, s53, 0xa000
	s_add_u32 s8, s8, 0x80
	s_mov_b32 m0, s63
	s_nop 0
	global_load_lds_dwordx4 v130, s[14:15]
	s_addc_u32 s9, s9, 0
	s_mov_b32 m0, s64
	s_nop 0
	global_load_lds_dwordx4 v130, s[12:13]
	s_add_u32 s10, s10, 0x80
	v_lshlrev_b32_e32 v2, 2, v2
	s_addc_u32 s11, s11, 0
	s_add_i32 s65, s53, 0x1c000
	s_mov_b32 m0, s65
	s_nop 0
	global_load_lds_dwordx4 v0, s[8:9]
	v_lshlrev_b32_e32 v3, 2, v3
	v_lshl_or_b32 v1, v1, 6, v6
	v_and_b32_e32 v2, 32, v2
	s_add_i32 s66, s53, 0x1e000
	s_mov_b32 m0, s66
	s_nop 0
	global_load_lds_dwordx4 v0, s[10:11]
	v_and_b32_e32 v3, 32, v3
	v_bitop3_b32 v1, v1, v4, v2 bitop3:0xde
	s_waitcnt vmcnt(8)
	s_barrier
	s_waitcnt vmcnt(6)
	s_add_i32 s67, s53, 0xc000
	s_add_i32 s73, s53, 0xe000
	v_readlane_b32 s0, v254, 0
	v_mov_b32_e32 v131, v0
	v_bitop3_b32 v3, v5, v7, v3 bitop3:0xde
	s_cmpk_lt_u32 s0, 0x100
	v_add_u32_e32 v0, 0, v1
	s_cselect_b64 s[24:25], -1, 0
	v_add_u32_e32 v137, 0x10000, v0
	v_add_u32_e32 v138, 0x14000, v0
	v_add_u32_e32 v139, 0, v3
	v_add_u32_e32 v140, 0x18000, v0
	v_add_u32_e32 v141, 0x1c000, v0
	s_mov_b32 s79, s1
	s_barrier
	s_branch .LBB0_291

.Lsprio_4:
	s_cmp_lg_u32 s99, 0
	s_mov_b32 m0, s54
	s_nop 0
	global_load_lds_dwordx4 v0, s[8:9]
	s_add_u32 s8, s4, 0x80
	s_mov_b32 m0, s55
	s_nop 0
	global_load_lds_dwordx4 v0, s[22:23]
	s_addc_u32 s9, s5, 0
	s_sub_u32 s2, 0, s34
	s_subb_u32 s22, 0, s35
	s_add_u32 s2, s14, s2
	s_addc_u32 s15, s15, s22
	s_add_u32 s14, s2, 0x80
	s_addc_u32 s15, s15, 0
	s_add_i32 s56, s53, 0x8000
	s_add_i32 s61, s53, 0xa000
	s_mov_b32 m0, s56
	s_nop 0
	global_load_lds_dwordx4 v160, s[8:9]
	s_add_u32 s8, s10, 0x80
	s_addc_u32 s9, s11, 0
	s_mov_b32 m0, s61
	s_nop 0
	global_load_lds_dwordx4 v160, s[14:15]
	s_add_u32 s10, s12, 0x80
	v_lshlrev_b32_e32 v2, 2, v2
	s_addc_u32 s11, s13, 0
	s_add_i32 s62, s53, 0x1c000
	s_mov_b32 m0, s62
	s_nop 0
	global_load_lds_dwordx4 v0, s[8:9]
	v_lshlrev_b32_e32 v3, 2, v3
	v_lshl_or_b32 v1, v1, 6, v6
	v_and_b32_e32 v2, 32, v2
	s_add_i32 s63, s53, 0x1e000
	s_mov_b32 m0, s63
	s_nop 0
	global_load_lds_dwordx4 v0, s[10:11]
	v_and_b32_e32 v3, 32, v3
	v_bitop3_b32 v1, v1, v4, v2 bitop3:0xde
	s_waitcnt vmcnt(8)
	s_barrier
	s_waitcnt vmcnt(6)
	s_add_i32 s64, s53, 0xc000
	s_add_i32 s65, s53, 0xe000
	v_readlane_b32 s2, v254, 0
	v_mov_b32_e32 v161, v0
	v_bitop3_b32 v3, v5, v7, v3 bitop3:0xde
	s_cmpk_lt_u32 s2, 0x100
	v_add_u32_e32 v0, 0, v1
	s_mov_b32 s23, 0
	s_cselect_b64 s[24:25], -1, 0
	v_add_u32_e32 v194, 0x10000, v0
	v_add_u32_e32 v248, 0x14000, v0
	v_add_u32_e32 v249, 0, v3
	v_mov_b32_e32 v250, 0x79797979
	v_mov_b32_e32 v251, 0x7f7f7f7f
	v_add_u32_e32 v252, 0x18000, v0
	v_add_u32_e32 v253, 0x1c000, v0
	s_mov_b32 s67, 0
	s_barrier
	s_branch .LBB0_310

.Lsprio_5:
	s_cmp_lg_u32 s99, 0
	s_addc_u32 s23, s23, 0
	s_add_i32 s63, s54, 0x18000
	s_mov_b32 m0, s63
	s_nop 0
	global_load_lds_dwordx4 v0, s[8:9]
	s_add_i32 s64, s54, 0x1a000
	s_mov_b32 m0, s64
	s_nop 0
	global_load_lds_dwordx4 v0, s[22:23]
	s_add_u32 s8, s4, 0x80
	s_addc_u32 s9, s5, 0
	s_sub_u32 s22, 0, s48
	s_subb_u32 s23, 0, s49
	s_add_u32 s14, s14, s22
	s_addc_u32 s15, s15, s23
	s_add_u32 s14, s14, 0x80
	s_addc_u32 s15, s15, 0
	s_add_i32 s65, s54, 0x8000
	s_mov_b32 m0, s65
	s_nop 0
	global_load_lds_dwordx4 v128, s[8:9]
	s_add_i32 s66, s54, 0xa000
	s_mov_b32 m0, s66
	s_nop 0
	global_load_lds_dwordx4 v128, s[14:15]
	s_add_u32 s8, s10, 0x80
	s_addc_u32 s9, s11, 0
	s_add_u32 s10, s12, 0x80
	v_ashrrev_i32_e32 v4, 6, v2
	v_writelane_b32 v254, s3, 55
	v_lshlrev_b32_e32 v3, 2, v3
	s_addc_u32 s11, s13, 0
	s_add_i32 s67, s54, 0x1c000
	s_mov_b32 m0, s67
	s_nop 0
	global_load_lds_dwordx4 v0, s[8:9]
	v_lshl_add_u32 v7, v4, 10, s3
	v_and_b32_e32 v3, 32, v3
	v_writelane_b32 v254, s26, 61
	v_lshlrev_b32_e32 v2, 2, v2
	s_add_i32 s68, s54, 0x1e000
	s_mov_b32 m0, s68
	s_nop 0
	global_load_lds_dwordx4 v0, s[10:11]
	v_mov_b32_e32 v120, 0
	v_bitop3_b32 v151, v5, v7, v3 bitop3:0xde
	v_lshl_or_b32 v1, v1, 6, v6
	v_add_lshl_u32 v3, v4, s26, 10
	v_and_b32_e32 v2, 32, v2
	s_waitcnt vmcnt(8)
	s_barrier
	s_waitcnt vmcnt(6)
	s_add_i32 s69, s54, 0xc000
	s_add_i32 s70, s54, 0xe000
	v_readlane_b32 s2, v254, 0
	v_mov_b32_e32 v121, v120
	v_mov_b32_e32 v122, v120
	v_mov_b32_e32 v123, v120
	v_mov_b32_e32 v129, v0
	v_bitop3_b32 v152, v1, v3, v2 bitop3:0xde
	s_cmpk_lt_u32 s2, 0x100
	v_mov_b64_e32 v[126:127], v[122:123]
	v_mov_b64_e32 v[116:117], v[120:121]
	v_mov_b64_e32 v[108:109], v[120:121]
	v_mov_b64_e32 v[100:101], v[120:121]
	v_mov_b64_e32 v[92:93], v[120:121]
	v_mov_b64_e32 v[84:85], v[120:121]
	v_mov_b64_e32 v[76:77], v[120:121]
	v_mov_b64_e32 v[72:73], v[120:121]
	v_mov_b64_e32 v[64:65], v[120:121]
	v_mov_b64_e32 v[56:57], v[120:121]
	v_mov_b64_e32 v[44:45], v[120:121]
	v_mov_b64_e32 v[36:37], v[120:121]
	v_mov_b64_e32 v[28:29], v[120:121]
	v_mov_b64_e32 v[20:21], v[120:121]
	v_mov_b64_e32 v[12:13], v[120:121]
	v_mov_b64_e32 v[112:113], v[120:121]
	v_mov_b64_e32 v[104:105], v[120:121]
	v_mov_b64_e32 v[96:97], v[120:121]
	v_mov_b64_e32 v[88:89], v[120:121]
	v_mov_b64_e32 v[80:81], v[120:121]
	v_mov_b64_e32 v[68:69], v[120:121]
	v_mov_b64_e32 v[60:61], v[120:121]
	v_mov_b64_e32 v[52:53], v[120:121]
	v_mov_b64_e32 v[48:49], v[120:121]
	v_mov_b64_e32 v[40:41], v[120:121]
	v_mov_b64_e32 v[32:33], v[120:121]
	v_mov_b64_e32 v[24:25], v[120:121]
	v_mov_b64_e32 v[16:17], v[120:121]
	v_mov_b64_e32 v[8:9], v[120:121]
	v_mov_b64_e32 v[4:5], v[120:121]
	v_mov_b64_e32 v[0:1], v[120:121]
	s_cselect_b64 s[22:23], -1, 0
	s_add_i32 s71, s52, 0x80
	s_add_i32 s72, s52, 0xa0
	s_mov_b32 s25, 0
	v_mov_b64_e32 v[124:125], v[120:121]
	v_mov_b64_e32 v[118:119], v[122:123]
	v_mov_b64_e32 v[110:111], v[122:123]
	v_mov_b64_e32 v[102:103], v[122:123]
	v_mov_b64_e32 v[94:95], v[122:123]
	v_mov_b64_e32 v[86:87], v[122:123]
	v_mov_b64_e32 v[78:79], v[122:123]
	v_mov_b64_e32 v[74:75], v[122:123]
	v_mov_b64_e32 v[66:67], v[122:123]
	v_mov_b64_e32 v[58:59], v[122:123]
	v_mov_b64_e32 v[46:47], v[122:123]
	v_mov_b64_e32 v[38:39], v[122:123]
	v_mov_b64_e32 v[30:31], v[122:123]
	v_mov_b64_e32 v[22:23], v[122:123]
	v_mov_b64_e32 v[14:15], v[122:123]
	v_mov_b64_e32 v[114:115], v[122:123]
	v_mov_b64_e32 v[106:107], v[122:123]
	v_mov_b64_e32 v[98:99], v[122:123]
	v_mov_b64_e32 v[90:91], v[122:123]
	v_mov_b64_e32 v[82:83], v[122:123]
	v_mov_b64_e32 v[70:71], v[122:123]
	v_mov_b64_e32 v[62:63], v[122:123]
	v_mov_b64_e32 v[54:55], v[122:123]
	v_mov_b64_e32 v[50:51], v[122:123]
	v_mov_b64_e32 v[42:43], v[122:123]
	v_mov_b64_e32 v[34:35], v[122:123]
	v_mov_b64_e32 v[26:27], v[122:123]
	v_mov_b64_e32 v[18:19], v[122:123]
	v_mov_b64_e32 v[10:11], v[122:123]
	v_mov_b64_e32 v[6:7], v[122:123]
	v_mov_b64_e32 v[2:3], v[122:123]
	s_mov_b32 s36, s31
	s_mov_b32 s31, 0
	s_barrier
	s_branch .LBB0_446

.Lsprio_6:
	s_cmp_lg_u32 s99, 0
	s_addc_u32 s15, s15, 0
	s_add_i32 s61, s54, 0x18000
	s_mov_b32 m0, s61
	s_nop 0
	global_load_lds_dwordx4 v0, s[2:3]
	s_add_i32 s62, s54, 0x1a000
	s_mov_b32 m0, s62
	s_nop 0
	global_load_lds_dwordx4 v0, s[14:15]
	s_add_u32 s2, s4, 0x80
	s_addc_u32 s3, s5, 0
	s_sub_u32 s14, 0, s36
	s_subb_u32 s15, 0, s37
	s_add_u32 s12, s12, s14
	s_addc_u32 s13, s13, s15
	s_add_u32 s12, s12, 0x80
	s_addc_u32 s13, s13, 0
	s_add_i32 s63, s54, 0x8000
	s_mov_b32 m0, s63
	s_nop 0
	global_load_lds_dwordx4 v160, s[2:3]
	s_add_i32 s64, s54, 0xa000
	s_mov_b32 m0, s64
	s_nop 0
	global_load_lds_dwordx4 v160, s[12:13]
	s_add_u32 s2, s8, 0x80
	s_addc_u32 s3, s9, 0
	s_add_u32 s8, s10, 0x80
	v_lshlrev_b32_e32 v2, 2, v2
	s_addc_u32 s9, s11, 0
	s_add_i32 s65, s54, 0x1c000
	s_mov_b32 m0, s65
	s_nop 0
	global_load_lds_dwordx4 v0, s[2:3]
	v_lshlrev_b32_e32 v3, 2, v3
	v_lshl_or_b32 v1, v1, 6, v6
	v_add_lshl_u32 v4, v4, s26, 10
	v_and_b32_e32 v2, 32, v2
	s_add_i32 s66, s54, 0x1e000
	s_mov_b32 m0, s66
	s_nop 0
	global_load_lds_dwordx4 v0, s[8:9]
	v_and_b32_e32 v3, 32, v3
	v_bitop3_b32 v1, v1, v4, v2 bitop3:0xde
	s_waitcnt vmcnt(8)
	s_barrier
	s_waitcnt vmcnt(6)
	s_add_i32 s67, s54, 0xc000
	s_add_i32 s73, s54, 0xe000
	v_readlane_b32 s2, v254, 0
	v_mov_b32_e32 v161, v0
	v_bitop3_b32 v3, v5, v7, v3 bitop3:0xde
	s_cmpk_lt_u32 s2, 0x100
	v_add_u32_e32 v0, 0, v1
	s_cselect_b64 s[26:27], -1, 0
	v_add_u32_e32 v194, 0x10000, v0
	v_add_u32_e32 v248, 0x14000, v0
	v_add_u32_e32 v249, 0, v3
	v_mov_b32_e32 v250, 0x79797979
	v_mov_b32_e32 v251, 0x7f7f7f7f
	v_add_u32_e32 v252, 0x18000, v0
	v_add_u32_e32 v253, 0x1c000, v0
	s_mov_b32 s79, s17
	s_barrier
	s_branch .LBB0_465

.Lsprio_7:
	s_cmp_lg_u32 s99, 0
	s_addc_u32 s25, s25, 0
	s_add_i32 s62, s57, 0x18000
	s_mov_b32 m0, s62
	s_nop 0
	global_load_lds_dwordx4 v0, s[8:9]
	s_add_i32 s63, s57, 0x1a000
	s_mov_b32 m0, s63
	s_nop 0
	global_load_lds_dwordx4 v0, s[24:25]
	s_add_u32 s8, s4, 0x80
	s_addc_u32 s9, s5, 0
	s_sub_u32 s24, 0, s38
	s_subb_u32 s25, 0, s39
	s_add_u32 s14, s14, s24
	s_addc_u32 s15, s15, s25
	s_add_u32 s14, s14, 0x80
	s_addc_u32 s15, s15, 0
	s_add_i32 s64, s57, 0x8000
	s_mov_b32 m0, s64
	s_nop 0
	global_load_lds_dwordx4 v128, s[8:9]
	s_add_i32 s65, s57, 0xa000
	s_mov_b32 m0, s65
	s_nop 0
	global_load_lds_dwordx4 v128, s[14:15]
	s_add_u32 s8, s10, 0x80
	s_addc_u32 s9, s11, 0
	s_add_u32 s10, s12, 0x80
	v_ashrrev_i32_e32 v4, 6, v2
	v_lshlrev_b32_e32 v2, 2, v2
	s_addc_u32 s11, s13, 0
	s_add_i32 s66, s57, 0x1c000
	s_mov_b32 m0, s66
	s_nop 0
	global_load_lds_dwordx4 v0, s[8:9]
	v_lshl_add_u32 v7, v4, 10, s50
	v_lshlrev_b32_e32 v3, 2, v3
	v_lshl_or_b32 v1, v1, 6, v6
	v_add_lshl_u32 v4, v4, s51, 10
	v_and_b32_e32 v2, 32, v2
	s_add_i32 s67, s57, 0x1e000
	s_mov_b32 m0, s67
	s_nop 0
	global_load_lds_dwordx4 v0, s[10:11]
	v_and_b32_e32 v3, 32, v3
	v_bitop3_b32 v1, v1, v4, v2 bitop3:0xde
	s_waitcnt vmcnt(8)
	s_barrier
	s_waitcnt vmcnt(6)
	s_add_i32 s68, s57, 0xc000
	s_add_i32 s69, s57, 0xe000
	v_readlane_b32 s8, v254, 0
	v_mov_b32_e32 v129, v0
	v_bitop3_b32 v3, v5, v7, v3 bitop3:0xde
	s_cmpk_lt_u32 s8, 0x100
	v_add_u32_e32 v0, 0, v1
	s_cselect_b64 s[24:25], -1, 0
	s_mov_b32 s27, 0
	v_add_u32_e32 v135, 0x10000, v0
	v_add_u32_e32 v136, 0x14000, v0
	v_add_u32_e32 v137, 0, v3
	v_add_u32_e32 v138, 0x18000, v0
	v_add_u32_e32 v139, 0x1c000, v0
	s_mov_b32 s70, 0
	s_barrier
	s_branch .LBB0_679

.Lsprio_8:
	s_cmp_lg_u32 s99, 0
	s_mov_b32 m0, s67
	s_nop 0
	global_load_lds_dwordx4 v0, s[18:19]
	s_add_u32 s18, s4, 0x80
	s_mov_b32 m0, s73
	s_nop 0
	global_load_lds_dwordx4 v0, s[20:21]
	s_addc_u32 s19, s5, 0
	s_sub_u32 s0, 0, s52
	s_subb_u32 s2, 0, s53
	s_add_u32 s0, s16, s0
	s_addc_u32 s2, s17, s2
	s_add_u32 s16, s0, 0x80
	s_addc_u32 s17, s2, 0
	s_add_i32 s78, s57, 0x8000
	s_add_i32 s79, s57, 0xa000
	s_add_u32 s12, s12, 0x80
	s_mov_b32 m0, s78
	s_nop 0
	global_load_lds_dwordx4 v60, s[18:19]
	s_addc_u32 s13, s13, 0
	v_ashrrev_i32_e32 v4, 6, v2
	v_lshlrev_b32_e32 v3, 2, v3
	s_mov_b32 m0, s79
	s_nop 0
	global_load_lds_dwordx4 v60, s[16:17]
	s_add_u32 s14, s14, 0x80
	v_lshl_add_u32 v7, v4, 10, s50
	v_and_b32_e32 v3, 32, v3
	v_lshlrev_b32_e32 v2, 2, v2
	s_addc_u32 s15, s15, 0
	s_add_i32 s82, s57, 0x1c000
	s_mov_b32 m0, s82
	s_nop 0
	global_load_lds_dwordx4 v0, s[12:13]
	v_mov_b32_e32 v61, v0
	v_bitop3_b32 v149, v5, v7, v3 bitop3:0xde
	v_lshl_or_b32 v1, v1, 6, v6
	v_add_lshl_u32 v3, v4, s51, 10
	v_and_b32_e32 v2, 32, v2
	s_add_i32 s83, s57, 0x1e000
	s_mov_b32 m0, s83
	s_nop 0
	global_load_lds_dwordx4 v0, s[14:15]
	v_mov_b32_e32 v0, 0
	v_bitop3_b32 v150, v1, v3, v2 bitop3:0xde
	s_waitcnt vmcnt(8)
	s_barrier
	s_waitcnt vmcnt(6)
	s_add_i32 s84, s57, 0xc000
	s_add_i32 s85, s57, 0xe000
	v_mov_b32_e32 v2, v0
	v_mov_b32_e32 v3, v0
	v_readlane_b32 s0, v254, 0
	v_mov_b32_e32 v1, v0
	s_cmpk_lt_u32 s0, 0x100
	v_mov_b64_e32 v[14:15], v[2:3]
	v_mov_b64_e32 v[22:23], v[2:3]
	v_mov_b64_e32 v[54:55], v[2:3]
	v_mov_b64_e32 v[58:59], v[2:3]
	v_mov_b64_e32 v[78:79], v[2:3]
	v_mov_b64_e32 v[86:87], v[2:3]
	v_mov_b64_e32 v[118:119], v[2:3]
	v_mov_b64_e32 v[122:123], v[2:3]
	v_mov_b64_e32 v[38:39], v[2:3]
	v_mov_b64_e32 v[42:43], v[2:3]
	v_mov_b64_e32 v[126:127], v[2:3]
	v_mov_b64_e32 v[130:131], v[2:3]
	v_mov_b64_e32 v[102:103], v[2:3]
	v_mov_b64_e32 v[106:107], v[2:3]
	v_mov_b64_e32 v[134:135], v[2:3]
	v_mov_b64_e32 v[138:139], v[2:3]
	v_mov_b64_e32 v[114:115], v[2:3]
	v_mov_b64_e32 v[110:111], v[2:3]
	v_mov_b64_e32 v[70:71], v[2:3]
	v_mov_b64_e32 v[74:75], v[2:3]
	v_mov_b64_e32 v[50:51], v[2:3]
	v_mov_b64_e32 v[46:47], v[2:3]
	v_mov_b64_e32 v[6:7], v[2:3]
	v_mov_b64_e32 v[10:11], v[2:3]
	v_mov_b64_e32 v[98:99], v[2:3]
	v_mov_b64_e32 v[94:95], v[2:3]
	v_mov_b64_e32 v[82:83], v[2:3]
	v_mov_b64_e32 v[90:91], v[2:3]
	v_mov_b64_e32 v[34:35], v[2:3]
	v_mov_b64_e32 v[30:31], v[2:3]
	v_mov_b64_e32 v[18:19], v[2:3]
	v_mov_b64_e32 v[26:27], v[2:3]
	s_mov_b32 s44, s25
	s_mov_b32 s45, s26
	s_cselect_b64 s[26:27], -1, 0
	v_mov_b64_e32 v[12:13], v[0:1]
	v_mov_b64_e32 v[20:21], v[0:1]
	v_mov_b64_e32 v[52:53], v[0:1]
	v_mov_b64_e32 v[56:57], v[0:1]
	v_mov_b64_e32 v[76:77], v[0:1]
	v_mov_b64_e32 v[84:85], v[0:1]
	v_mov_b64_e32 v[116:117], v[0:1]
	v_mov_b64_e32 v[120:121], v[0:1]
	v_mov_b64_e32 v[36:37], v[0:1]
	v_mov_b64_e32 v[40:41], v[0:1]
	v_mov_b64_e32 v[124:125], v[0:1]
	v_mov_b64_e32 v[128:129], v[0:1]
	v_mov_b64_e32 v[100:101], v[0:1]
	v_mov_b64_e32 v[104:105], v[0:1]
	v_mov_b64_e32 v[132:133], v[0:1]
	v_mov_b64_e32 v[136:137], v[0:1]
	v_mov_b64_e32 v[112:113], v[0:1]
	v_mov_b64_e32 v[108:109], v[0:1]
	v_mov_b64_e32 v[68:69], v[0:1]
	v_mov_b64_e32 v[72:73], v[0:1]
	v_mov_b64_e32 v[48:49], v[0:1]
	v_mov_b64_e32 v[44:45], v[0:1]
	v_mov_b64_e32 v[4:5], v[0:1]
	v_mov_b64_e32 v[8:9], v[0:1]
	v_mov_b64_e32 v[96:97], v[0:1]
	v_mov_b64_e32 v[92:93], v[0:1]
	v_mov_b64_e32 v[80:81], v[0:1]
	v_mov_b64_e32 v[88:89], v[0:1]
	v_mov_b64_e32 v[32:33], v[0:1]
	v_mov_b64_e32 v[28:29], v[0:1]
	v_mov_b64_e32 v[16:17], v[0:1]
	v_mov_b64_e32 v[24:25], v[0:1]
	s_mov_b32 s2, s1
	s_barrier
	s_branch .LBB0_698

.Lsprio_9:
	s_cmp_lg_u32 s99, 0
	s_mov_b32 m0, s67
	s_nop 0
	global_load_lds_dwordx4 v0, s[16:17]
	s_add_u32 s16, s4, 0x80
	s_mov_b32 m0, s73
	s_nop 0
	global_load_lds_dwordx4 v0, s[20:21]
	s_addc_u32 s17, s5, 0
	s_sub_u32 s2, 0, s46
	s_subb_u32 s20, 0, s47
	s_add_u32 s2, s18, s2
	s_addc_u32 s19, s19, s20
	s_add_u32 s18, s2, 0x80
	s_addc_u32 s19, s19, 0
	s_add_i32 s78, s3, 0x8000
	s_add_i32 s79, s3, 0xa000
	s_add_u32 s12, s12, 0x80
	s_mov_b32 m0, s78
	s_nop 0
	global_load_lds_dwordx4 v128, s[16:17]
	s_addc_u32 s13, s13, 0
	s_mov_b32 m0, s79
	s_nop 0
	global_load_lds_dwordx4 v128, s[18:19]
	s_add_u32 s14, s14, 0x80
	v_lshlrev_b32_e32 v2, 2, v2
	s_addc_u32 s15, s15, 0
	s_add_i32 s82, s3, 0x1c000
	s_mov_b32 m0, s82
	s_nop 0
	global_load_lds_dwordx4 v0, s[12:13]
	v_and_b32_e32 v2, 32, v2
	s_add_i32 s83, s3, 0x1e000
	s_mov_b32 m0, s83
	s_nop 0
	global_load_lds_dwordx4 v0, s[14:15]
	v_bitop3_b32 v1, v3, v1, v2 bitop3:0xde
	s_waitcnt vmcnt(8)
	s_barrier
	s_waitcnt vmcnt(6)
	s_add_i32 s84, s3, 0xc000
	s_add_i32 s85, s3, 0xe000
	v_readlane_b32 s2, v254, 0
	v_mov_b32_e32 v129, v0
	v_bitop3_b32 v4, v3, v4, v2 bitop3:0xde
	s_cmpk_lt_u32 s2, 0x100
	v_add_u32_e32 v0, 0, v1
	s_mov_b32 s38, s25
	s_mov_b32 s39, s26
	s_mov_b32 s35, 0
	s_cselect_b64 s[36:37], -1, 0
	v_add_u32_e32 v137, 0x10000, v0
	v_add_u32_e32 v138, 0x14000, v0
	v_add_u32_e32 v139, 0, v4
	v_add_u32_e32 v140, 0x18000, v0
	v_add_u32_e32 v141, 0x1c000, v0
	s_mov_b32 s86, 0
	s_mov_b32 s26, s27
	s_barrier
	s_branch .LBB0_779

.Lsprio_10:
	s_cmp_lg_u32 s99, 0
	s_mov_b32 m0, s60
	s_nop 0
	global_load_lds_dwordx4 v0, s[8:9]
	s_add_u32 s8, s4, 0x80
	s_mov_b32 m0, s61
	s_nop 0
	global_load_lds_dwordx4 v0, s[22:23]
	s_addc_u32 s9, s5, 0
	s_sub_u32 s2, 0, s34
	s_subb_u32 s22, 0, s35
	s_add_u32 s2, s14, s2
	s_addc_u32 s15, s15, s22
	s_add_u32 s14, s2, 0x80
	s_addc_u32 s15, s15, 0
	s_add_i32 s62, s55, 0x8000
	s_add_i32 s63, s55, 0xa000
	s_mov_b32 m0, s62
	s_nop 0
	global_load_lds_dwordx4 v128, s[8:9]
	s_add_u32 s8, s10, 0x80
	s_addc_u32 s9, s11, 0
	s_mov_b32 m0, s63
	s_nop 0
	global_load_lds_dwordx4 v128, s[14:15]
	s_add_u32 s10, s12, 0x80
	v_ashrrev_i32_e32 v4, 6, v2
	v_lshlrev_b32_e32 v2, 2, v2
	s_addc_u32 s11, s13, 0
	s_add_i32 s64, s55, 0x1c000
	s_mov_b32 m0, s64
	s_nop 0
	global_load_lds_dwordx4 v0, s[8:9]
	v_lshl_add_u32 v7, v4, 10, s46
	v_lshlrev_b32_e32 v3, 2, v3
	v_lshl_or_b32 v1, v1, 6, v6
	v_add_lshl_u32 v4, v4, s47, 10
	v_and_b32_e32 v2, 32, v2
	s_add_i32 s65, s55, 0x1e000
	s_mov_b32 m0, s65
	s_nop 0
	global_load_lds_dwordx4 v0, s[10:11]
	v_and_b32_e32 v3, 32, v3
	v_bitop3_b32 v1, v1, v4, v2 bitop3:0xde
	s_waitcnt vmcnt(8)
	s_barrier
	s_waitcnt vmcnt(6)
	s_add_i32 s66, s55, 0xc000
	s_add_i32 s67, s55, 0xe000
	v_readlane_b32 s2, v254, 0
	v_mov_b32_e32 v129, v0
	v_bitop3_b32 v3, v5, v7, v3 bitop3:0xde
	s_cmpk_lt_u32 s2, 0x100
	v_add_u32_e32 v0, 0, v1
	s_mov_b32 s23, 0
	s_cselect_b64 s[24:25], -1, 0
	v_add_u32_e32 v133, 0x10000, v0
	v_add_u32_e32 v134, 0x14000, v0
	v_add_u32_e32 v135, 0, v3
	v_add_u32_e32 v136, 0x18000, v0
	v_add_u32_e32 v137, 0x1c000, v0
	s_mov_b32 s73, 0
	s_barrier
	s_branch .LBB0_919

.Lsprio_11:
	s_cmp_lg_u32 s99, 0
	s_mov_b32 m0, s65
	s_nop 0
	global_load_lds_dwordx4 v0, s[18:19]
	s_add_u32 s18, s4, 0x80
	s_mov_b32 m0, s66
	s_nop 0
	global_load_lds_dwordx4 v0, s[20:21]
	s_addc_u32 s19, s5, 0
	s_sub_u32 s2, 0, s50
	s_subb_u32 s20, 0, s51
	s_add_u32 s2, s16, s2
	s_addc_u32 s17, s17, s20
	s_add_u32 s16, s2, 0x80
	s_addc_u32 s17, s17, 0
	s_add_i32 s67, s55, 0x8000
	s_add_i32 s73, s55, 0xa000
	s_add_u32 s12, s12, 0x80
	s_mov_b32 m0, s67
	s_nop 0
	global_load_lds_dwordx4 v160, s[18:19]
	s_addc_u32 s13, s13, 0
	s_mov_b32 m0, s73
	s_nop 0
	global_load_lds_dwordx4 v160, s[16:17]
	s_add_u32 s14, s14, 0x80
	v_ashrrev_i32_e32 v4, 6, v2
	v_lshlrev_b32_e32 v2, 2, v2
	s_addc_u32 s15, s15, 0
	s_add_i32 s78, s55, 0x1c000
	s_mov_b32 m0, s78
	s_nop 0
	global_load_lds_dwordx4 v0, s[12:13]
	v_lshl_add_u32 v7, v4, 10, s46
	v_lshlrev_b32_e32 v3, 2, v3
	v_lshl_or_b32 v1, v1, 6, v6
	v_add_lshl_u32 v4, v4, s47, 10
	v_and_b32_e32 v2, 32, v2
	s_add_i32 s79, s55, 0x1e000
	s_mov_b32 m0, s79
	s_nop 0
	global_load_lds_dwordx4 v0, s[14:15]
	v_and_b32_e32 v3, 32, v3
	v_bitop3_b32 v1, v1, v4, v2 bitop3:0xde
	s_waitcnt vmcnt(8)
	s_barrier
	s_waitcnt vmcnt(6)
	s_add_i32 s82, s55, 0xc000
	s_add_i32 s83, s55, 0xe000
	v_readlane_b32 s2, v254, 0
	v_mov_b32_e32 v161, v0
	v_bitop3_b32 v3, v5, v7, v3 bitop3:0xde
	s_cmpk_lt_u32 s2, 0x100
	v_add_u32_e32 v0, 0, v1
	s_mov_b32 s42, s25
	s_mov_b32 s43, s26
	s_cselect_b64 s[26:27], -1, 0
	v_add_u32_e32 v251, 0x10000, v0
	v_add_u32_e32 v252, 0x14000, v0
	v_add_u32_e32 v253, 0, v3
	v_mov_b32_e32 v250, 0x79797979
	v_mov_b32_e32 v248, 0x7f7f7f7f
	v_add_u32_e32 v249, 0x18000, v0
	v_add_u32_e32 v162, 0x1c000, v0
	s_mov_b32 s84, s29
	s_barrier
	s_branch .LBB0_938

.Lsprio_12:
	s_cmp_lg_u32 s99, 0
	s_mov_b32 m0, s9
	s_nop 0
	global_load_lds_dwordx4 v0, s[12:13]
	s_add_u32 s12, s4, 0xffffff80
	s_addc_u32 s13, s5, -1
	s_mov_b32 m0, s80
	s_nop 0
	global_load_lds_dwordx4 v0, s[16:17]
	s_add_u32 s16, s12, s52
	s_addc_u32 s17, s13, s53
	s_add_i32 s81, s3, 0x8000
	s_add_i32 s82, s3, 0xa000
	s_mov_b32 m0, s81
	s_nop 0
	global_load_lds_dwordx4 v128, s[12:13]
	s_add_u32 s12, s14, 0xffffff80
	s_addc_u32 s13, s15, -1
	s_mov_b32 m0, s82
	s_nop 0
	global_load_lds_dwordx4 v128, s[16:17]
	s_add_u32 s14, s12, s34
	s_addc_u32 s15, s13, s35
	s_add_i32 s83, s3, 0x1c000
	s_mov_b32 m0, s83
	s_nop 0
	global_load_lds_dwordx4 v0, s[12:13]
	v_lshlrev_b32_e32 v2, 2, v2
	s_add_i32 s84, s3, 0x1e000
	s_mov_b32 m0, s84
	s_nop 0
	global_load_lds_dwordx4 v0, s[14:15]
	v_and_b32_e32 v2, 32, v2
	v_add_lshl_u32 v1, v1, s11, 10
	v_readlane_b32 s0, v254, 0
	v_writelane_b32 v254, s12, 55
	v_bitop3_b32 v1, v3, v1, v2 bitop3:0xde
	s_waitcnt vmcnt(8)
	s_barrier
	s_waitcnt vmcnt(6)
	s_add_i32 s85, s3, 0xc000
	s_add_i32 s86, s3, 0xe000
	v_writelane_b32 v254, s13, 56
	v_mov_b32_e32 v129, v0
	v_bitop3_b32 v4, v3, v4, v2 bitop3:0xde
	s_movk_i32 s46, 0xff80
	s_cmpk_lt_u32 s0, 0x100
	v_add_u32_e32 v0, 0, v1
	v_writelane_b32 v254, s14, 57
	s_mov_b32 s47, -1
	s_mov_b32 s11, 0
	s_cselect_b64 s[36:37], -1, 0
	v_add_u32_e32 v173, 0x10000, v0
	v_add_u32_e32 v174, 0x14000, v0
	v_add_u32_e32 v175, 0, v4
	v_add_u32_e32 v176, 0x18000, v0
	v_add_u32_e32 v177, 0x1c000, v0
	v_mov_b32_e32 v161, 0
	v_writelane_b32 v254, s15, 58
	s_mov_b32 s77, 0
	s_mov_b32 s22, s1
	s_barrier
	s_branch .LBB0_1014
